# v31 + residual epilogue stages the next row-group pair's f16 residual loads during processing (1 exposed round trip per tile instead of 4)
# speedup vs baseline: 1.0006x; 1.0006x over previous
;     __device__ __forceinline__ void operator()(const f32x4 (&acc)[2][2][4][2], const Unit& u, int wr, int wc, int fr, int fq) const {
;         const int row0 = u.pm * BM + wr * 64 + fr, col0 = u.pn * BM + wc * 32 + 8 * fq;
; #pragma unroll
;         for (int ai = 0; ai < 2; ++ai)
; #pragma unroll
;         for (int mh = 0; mh < 2; ++mh) {
;             f32x8v pre[2][2];
;             if (base32) {
; #pragma unroll
;                 for (int mm = 0; mm < 2; ++mm) { const size_t off = (size_t)(row0 + ai * HALF + (2 * mh + mm) * 16) * ldc + col0;
; #pragma unroll
;                     for (int bj = 0; bj < 2; ++bj) { const f32x4 a0 = *(const f32x4*)(base32 + off + bj * HALF), a1 = *(const f32x4*)(base32 + off + bj * HALF + 4);
;                         pre[mm][bj] = __builtin_shufflevector(a0, a1, 0, 1, 2, 3, 4, 5, 6, 7); } }
;             } else if (pf & 1) {
; #pragma unroll
;                 for (int mm = 0; mm < 2; ++mm)
; #pragma unroll
;                     for (int bj = 0; bj < 2; ++bj) pre[mm][bj] = (f32x8v){0, 0, 0, 0, 0, 0, 0, 0};
;             } else {
;                 f16x8v ph[2][2];
; #pragma unroll
;                 for (int mm = 0; mm < 2; ++mm) { const size_t off = (size_t)(row0 + ai * HALF + (2 * mh + mm) * 16) * ldc + col0;
; #pragma unroll
;                     for (int bj = 0; bj < 2; ++bj) ph[mm][bj] = *(const f16x8v*)(xh + off + bj * HALF); }
; #pragma unroll
;                 for (int mm = 0; mm < 2; ++mm)
; #pragma unroll
;                     for (int bj = 0; bj < 2; ++bj) pre[mm][bj] = __builtin_convertvector(ph[mm][bj], f32x8v);
;             }
; #pragma unroll
;             for (int mm = 0; mm < 2; ++mm) {
;                 const int m = 2 * mh + mm;
;                 const int row = row0 + ai * HALF + m * 16; const size_t off = (size_t)row * ldc + col0;
;                 float q = 0.f;
; #pragma unroll
;                 for (int bj = 0; bj < 2; ++bj) {
;                     const f32x8v o = pre[mm][bj] + __builtin_shufflevector(acc[ai][bj][m][0], acc[ai][bj][m][1], 0, 1, 2, 3, 4, 5, 6, 7);
;                     if (!(pf & 2)) *(f16x8v*)(xh + off + bj * HALF) = __builtin_convertvector(o, f16x8v);
;                     q += ((o[0] * o[0] + o[1] * o[1]) + (o[2] * o[2] + o[3] * o[3])) + ((o[4] * o[4] + o[5] * o[5]) + (o[6] * o[6] + o[7] * o[7]));
;                 }
.LBB0_348:
	v_lshl_or_b32 v148, s24, 8, v159
	v_lshl_add_u32 v150, s78, 8, v1
	v_ashrrev_i32_e32 v149, 31, v148
	v_lshlrev_b64 v[170:171], 1, v[148:149]
	v_ashrrev_i32_e32 v151, 31, v150
	v_lshl_add_u64 v[152:153], s[0:1], 0, v[170:171]
	v_lshlrev_b64 v[172:173], 12, v[150:151]
	v_lshl_add_u64 v[130:131], v[152:153], 0, v[172:173]
	v_mov_b64_e32 v[222:223], v[130:131]
	global_load_dwordx4 v[162:165], v[130:131], off
	global_load_dwordx4 v[166:169], v[130:131], off offset:256
	v_or_b32_e32 v154, 16, v150
	v_ashrrev_i32_e32 v155, 31, v154
	v_lshlrev_b64 v[156:157], 12, v[154:155]
	v_lshl_add_u64 v[130:131], v[152:153], 0, v[156:157]
	global_load_dwordx4 v[134:137], v[130:131], off
	s_nop 0
	global_load_dwordx4 v[130:133], v[130:131], off offset:256
	s_mov_b32 s54, 0x20000
	s_mov_b32 s55, 0
	v_lshl_add_u64 v[220:221], v[222:223], 0, s[54:55]
	global_load_dwordx4 v[204:207], v[220:221], off
	global_load_dwordx4 v[208:211], v[220:221], off offset:256
	s_mov_b32 s54, 0x30000
	v_lshl_add_u64 v[220:221], v[222:223], 0, s[54:55]
	global_load_dwordx4 v[212:215], v[220:221], off
	global_load_dwordx4 v[216:219], v[220:221], off offset:256
	v_and_b32_e32 v176, 64, v200
	v_xor_b32_e32 v161, 16, v200
	v_add_u32_e32 v176, 64, v176
	v_xor_b32_e32 v177, 32, v200
	v_cmp_lt_i32_e32 vcc, v161, v176
	v_lshl_add_u64 v[172:173], s[0:1], 0, v[172:173]
	v_lshl_add_u64 v[170:171], v[172:173], 0, v[170:171]
	v_cndmask_b32_e32 v161, v200, v161, vcc
	v_cmp_lt_i32_e32 vcc, v177, v176
	v_lshlrev_b32_e32 v161, 2, v161
	s_lshl_b32 s52, s24, 2
	v_cndmask_b32_e32 v188, v200, v177, vcc
	s_ashr_i32 s53, s52, 31
	s_waitcnt vmcnt(4)
	v_cvt_f32_f16_e32 v172, v165
	v_cvt_f32_f16_sdwa v173, v165 dst_sel:DWORD dst_unused:UNUSED_PAD src0_sel:WORD_1
	v_cvt_f32_f16_e32 v176, v164
	v_cvt_f32_f16_sdwa v177, v164 dst_sel:DWORD dst_unused:UNUSED_PAD src0_sel:WORD_1
	v_cvt_f32_f16_e32 v164, v163
	v_cvt_f32_f16_sdwa v165, v163 dst_sel:DWORD dst_unused:UNUSED_PAD src0_sel:WORD_1
	v_cvt_f32_f16_e32 v182, v162
	v_cvt_f32_f16_sdwa v183, v162 dst_sel:DWORD dst_unused:UNUSED_PAD src0_sel:WORD_1
	v_cvt_f32_f16_e32 v162, v169
	v_cvt_f32_f16_sdwa v163, v169 dst_sel:DWORD dst_unused:UNUSED_PAD src0_sel:WORD_1
	v_cvt_f32_f16_e32 v184, v168
	v_cvt_f32_f16_sdwa v185, v168 dst_sel:DWORD dst_unused:UNUSED_PAD src0_sel:WORD_1
	v_cvt_f32_f16_e32 v168, v167
	v_cvt_f32_f16_sdwa v169, v167 dst_sel:DWORD dst_unused:UNUSED_PAD src0_sel:WORD_1
	v_cvt_f32_f16_e32 v186, v166
	v_cvt_f32_f16_sdwa v187, v166 dst_sel:DWORD dst_unused:UNUSED_PAD src0_sel:WORD_1
	v_pk_add_f32 v[122:123], v[122:123], v[182:183]
	v_pk_add_f32 v[124:125], v[124:125], v[164:165]
	v_pk_add_f32 v[126:127], v[126:127], v[176:177]
	v_pk_add_f32 v[128:129], v[128:129], v[172:173]
	v_pk_add_f32 v[164:165], v[118:119], v[186:187]
	v_pk_add_f32 v[118:119], v[120:121], v[168:169]
	v_pk_add_f32 v[166:167], v[114:115], v[184:185]
	v_pk_add_f32 v[120:121], v[116:117], v[162:163]
	v_cvt_pk_f16_f32 v117, v128, v129
	v_cvt_pk_f16_f32 v116, v126, v127
	v_mul_f32_e32 v114, v123, v123
	v_mul_f32_e32 v115, v125, v125
	v_mul_f32_e32 v127, v127, v127
	v_mul_f32_e32 v129, v129, v129
	v_mul_f32_e32 v162, v165, v165
	v_mul_f32_e32 v163, v119, v119
	v_mul_f32_e32 v168, v167, v167
	v_mul_f32_e32 v169, v121, v121
	v_fmac_f32_e32 v114, v122, v122
	v_fmac_f32_e32 v115, v124, v124
	v_fmac_f32_e32 v127, v126, v126
	v_fmac_f32_e32 v129, v128, v128
	v_fmac_f32_e32 v162, v164, v164
	v_fmac_f32_e32 v163, v118, v118
	v_fmac_f32_e32 v168, v166, v166
	v_fmac_f32_e32 v169, v120, v120
	v_add_f32_e32 v114, v114, v115
	v_add_f32_e32 v115, v127, v129
	v_add_f32_e32 v126, v162, v163
	v_add_f32_e32 v127, v168, v169
	v_add_f32_e32 v114, v114, v115
	v_add_f32_e32 v115, v126, v127
	v_add_f32_e32 v126, v114, v115
	v_mov_b32_e32 v127, v126
	s_nop 1
	v_permlane16_swap_b32_e32 v127, v126
	v_cvt_pk_f16_f32 v115, v124, v125
	v_cvt_pk_f16_f32 v114, v122, v123
	global_store_dwordx4 v[170:171], v[114:117], off
	v_cvt_pk_f16_f32 v121, v120, v121
	v_cvt_pk_f16_f32 v120, v166, v167
	s_waitcnt lgkmcnt(0)
	v_add_f32_e32 v115, v126, v127
	v_lshlrev_b32_e32 v114, 2, v188
	v_mov_b32_e32 v116, v115
	s_nop 1
	v_permlane32_swap_b32_e32 v116, v115
	v_cvt_pk_f16_f32 v119, v118, v119
	v_cvt_pk_f16_f32 v118, v164, v165
	global_store_dwordx4 v[170:171], v[118:121], off offset:256
	s_and_saveexec_b64 s[54:55], s[36:37]
	s_cbranch_execz .LBB0_350
	v_lshlrev_b64 v[118:119], 7, v[150:151]
	v_lshl_add_u64 v[118:119], s[44:45], 0, v[118:119]
	v_lshl_add_u64 v[118:119], s[52:53], 2, v[118:119]
	s_lshl_b32 s24, s23, 2
	v_lshl_add_u64 v[118:119], v[118:119], 0, s[24:25]
	s_waitcnt lgkmcnt(0)
	v_add_f32_e32 v115, v115, v116
	global_store_dword v[118:119], v115, off

;     __device__ __forceinline__ void operator()(const f32x4 (&acc)[2][2][4][2], const Unit& u, int wr, int wc, int fr, int fq) const {
;     ...
;         for (int ai = 0; ai < 2; ++ai)
; #pragma unroll
;         for (int mh = 0; mh < 2; ++mh) {
;             f32x8v pre[2][2];
;             if (base32) {
; #pragma unroll
;                 for (int mm = 0; mm < 2; ++mm) { const size_t off = (size_t)(row0 + ai * HALF + (2 * mh + mm) * 16) * ldc + col0;
; #pragma unroll
;                     for (int bj = 0; bj < 2; ++bj) { const f32x4 a0 = *(const f32x4*)(base32 + off + bj * HALF), a1 = *(const f32x4*)(base32 + off + bj * HALF + 4);
;                         pre[mm][bj] = __builtin_shufflevector(a0, a1, 0, 1, 2, 3, 4, 5, 6, 7); } }
;             } else if (pf & 1) {
; #pragma unroll
;                 for (int mm = 0; mm < 2; ++mm)
; #pragma unroll
;                     for (int bj = 0; bj < 2; ++bj) pre[mm][bj] = (f32x8v){0, 0, 0, 0, 0, 0, 0, 0};
;             } else {
;                 f16x8v ph[2][2];
; #pragma unroll
;                 for (int mm = 0; mm < 2; ++mm) { const size_t off = (size_t)(row0 + ai * HALF + (2 * mh + mm) * 16) * ldc + col0;
; #pragma unroll
;                     for (int bj = 0; bj < 2; ++bj) ph[mm][bj] = *(const f16x8v*)(xh + off + bj * HALF); }
; #pragma unroll
;                 for (int mm = 0; mm < 2; ++mm)
; #pragma unroll
;                     for (int bj = 0; bj < 2; ++bj) pre[mm][bj] = __builtin_convertvector(ph[mm][bj], f32x8v);
;             }
; #pragma unroll
;             for (int mm = 0; mm < 2; ++mm) {
;                 const int m = 2 * mh + mm;
;                 const int row = row0 + ai * HALF + m * 16; const size_t off = (size_t)row * ldc + col0;
;                 float q = 0.f;
; #pragma unroll
;                 for (int bj = 0; bj < 2; ++bj) {
;                     const f32x8v o = pre[mm][bj] + __builtin_shufflevector(acc[ai][bj][m][0], acc[ai][bj][m][1], 0, 1, 2, 3, 4, 5, 6, 7);
;                     if (!(pf & 2)) *(f16x8v*)(xh + off + bj * HALF) = __builtin_convertvector(o, f16x8v);
;                     q += ((o[0] * o[0] + o[1] * o[1]) + (o[2] * o[2] + o[3] * o[3])) + ((o[4] * o[4] + o[5] * o[5]) + (o[6] * o[6] + o[7] * o[7]));
;                 }
;                 if (!(pf & 4)) { q += __shfl_xor(q, 16); q += __shfl_xor(q, 32);
;                 if (fq == 0) ssn[(size_t)row * 32 + u.pn * 4 + wc] = q; }
.LBB0_352:
	s_or_b64 exec, exec, s[54:55]
	v_or_b32_e32 v110, 32, v150
	v_ashrrev_i32_e32 v111, 31, v110
	v_lshlrev_b64 v[112:113], 12, v[110:111]
	s_waitcnt lgkmcnt(0)
	v_lshl_add_u64 v[98:99], v[152:153], 0, v[112:113]
	s_waitcnt vmcnt(4)
	v_mov_b64_e32 v[116:117], v[204:205]
	v_mov_b64_e32 v[118:119], v[206:207]
	v_mov_b64_e32 v[120:121], v[208:209]
	v_mov_b64_e32 v[122:123], v[210:211]
	v_or_b32_e32 v106, 48, v150
	v_ashrrev_i32_e32 v107, 31, v106
	v_lshlrev_b64 v[108:109], 12, v[106:107]
	v_lshl_add_u64 v[98:99], v[152:153], 0, v[108:109]
	v_mov_b64_e32 v[102:103], v[212:213]
	v_mov_b64_e32 v[104:105], v[214:215]
	s_nop 0
	v_mov_b64_e32 v[98:99], v[216:217]
	v_mov_b64_e32 v[100:101], v[218:219]
	s_mov_b32 s54, 0x80000
	s_mov_b32 s55, 0
	v_lshl_add_u64 v[220:221], v[222:223], 0, s[54:55]
	global_load_dwordx4 v[204:207], v[220:221], off
	global_load_dwordx4 v[208:211], v[220:221], off offset:256
	s_mov_b32 s54, 0x90000
	v_lshl_add_u64 v[220:221], v[222:223], 0, s[54:55]
	global_load_dwordx4 v[212:215], v[220:221], off
	global_load_dwordx4 v[216:219], v[220:221], off offset:256
	v_cvt_f32_f16_e32 v124, v119
	v_cvt_f32_f16_sdwa v125, v119 dst_sel:DWORD dst_unused:UNUSED_PAD src0_sel:WORD_1
	v_cvt_f32_f16_e32 v126, v118
	v_cvt_f32_f16_sdwa v127, v118 dst_sel:DWORD dst_unused:UNUSED_PAD src0_sel:WORD_1
	v_cvt_f32_f16_e32 v118, v117
	v_cvt_f32_f16_sdwa v119, v117 dst_sel:DWORD dst_unused:UNUSED_PAD src0_sel:WORD_1
	v_cvt_f32_f16_e32 v128, v116
	v_cvt_f32_f16_sdwa v129, v116 dst_sel:DWORD dst_unused:UNUSED_PAD src0_sel:WORD_1
	v_cvt_f32_f16_e32 v116, v123
	v_cvt_f32_f16_sdwa v117, v123 dst_sel:DWORD dst_unused:UNUSED_PAD src0_sel:WORD_1
	v_cvt_f32_f16_e32 v130, v122
	v_cvt_f32_f16_sdwa v131, v122 dst_sel:DWORD dst_unused:UNUSED_PAD src0_sel:WORD_1
	v_cvt_f32_f16_e32 v122, v121
	v_cvt_f32_f16_sdwa v123, v121 dst_sel:DWORD dst_unused:UNUSED_PAD src0_sel:WORD_1
	v_cvt_f32_f16_e32 v132, v120
	v_cvt_f32_f16_sdwa v133, v120 dst_sel:DWORD dst_unused:UNUSED_PAD src0_sel:WORD_1
	v_pk_add_f32 v[94:95], v[94:95], v[128:129]
	v_pk_add_f32 v[96:97], v[96:97], v[118:119]
	v_pk_add_f32 v[90:91], v[90:91], v[126:127]
	v_pk_add_f32 v[92:93], v[92:93], v[124:125]
	v_pk_add_f32 v[118:119], v[86:87], v[132:133]
	v_pk_add_f32 v[88:89], v[88:89], v[122:123]
	v_pk_add_f32 v[120:121], v[82:83], v[130:131]
	v_pk_add_f32 v[86:87], v[84:85], v[116:117]
	v_cvt_pk_f16_f32 v85, v92, v93
	v_cvt_pk_f16_f32 v84, v90, v91
	v_cvt_pk_f16_f32 v83, v96, v97
	v_cvt_pk_f16_f32 v82, v94, v95
	v_mul_f32_e32 v95, v95, v95
	v_mul_f32_e32 v97, v97, v97
	v_mul_f32_e32 v91, v91, v91
	v_mul_f32_e32 v93, v93, v93
	v_mul_f32_e32 v115, v119, v119
	v_mul_f32_e32 v116, v89, v89
	v_mul_f32_e32 v117, v121, v121
	v_mul_f32_e32 v122, v87, v87
	v_fmac_f32_e32 v95, v94, v94
	v_fmac_f32_e32 v97, v96, v96
	v_fmac_f32_e32 v91, v90, v90
	v_fmac_f32_e32 v93, v92, v92
	v_fmac_f32_e32 v115, v118, v118
	v_fmac_f32_e32 v116, v88, v88
	v_fmac_f32_e32 v117, v120, v120
	v_fmac_f32_e32 v122, v86, v86
	v_add_f32_e32 v90, v95, v97
	v_add_f32_e32 v91, v91, v93
	v_add_f32_e32 v92, v115, v116
	v_add_f32_e32 v93, v117, v122
	v_add_f32_e32 v90, v90, v91
	v_add_f32_e32 v91, v92, v93
	v_add_f32_e32 v92, v90, v91
	v_mov_b32_e32 v93, v92
	s_nop 1
	v_permlane16_swap_b32_e32 v93, v92
	v_lshl_add_u64 v[90:91], s[0:1], 0, v[112:113]
	v_lshl_add_u64 v[90:91], v[148:149], 1, v[90:91]
	global_store_dwordx4 v[90:91], v[82:85], off
	v_cvt_pk_f16_f32 v87, v86, v87
	v_cvt_pk_f16_f32 v86, v120, v121
	s_waitcnt lgkmcnt(0)
	v_add_f32_e32 v82, v92, v93
	v_mov_b32_e32 v83, v82
	s_nop 1
	v_permlane32_swap_b32_e32 v83, v82
	v_cvt_pk_f16_f32 v85, v88, v89
	v_cvt_pk_f16_f32 v84, v118, v119
	global_store_dwordx4 v[90:91], v[84:87], off offset:256
	s_and_saveexec_b64 s[54:55], s[36:37]
	s_cbranch_execz .LBB0_354
	v_lshlrev_b64 v[84:85], 7, v[110:111]
	v_lshl_add_u64 v[84:85], s[44:45], 0, v[84:85]
	v_lshl_add_u64 v[84:85], s[52:53], 2, v[84:85]
	s_lshl_b32 s24, s23, 2
	v_lshl_add_u64 v[84:85], v[84:85], 0, s[24:25]
	s_waitcnt lgkmcnt(0)
	v_add_f32_e32 v82, v82, v83
	global_store_dword v[84:85], v82, off
.LBB0_354:
	s_or_b64 exec, exec, s[54:55]
	v_cvt_f32_f16_sdwa v89, v102 dst_sel:DWORD dst_unused:UNUSED_PAD src0_sel:WORD_1
	v_cvt_f32_f16_e32 v88, v102
	v_cvt_f32_f16_sdwa v85, v104 dst_sel:DWORD dst_unused:UNUSED_PAD src0_sel:WORD_1
	v_cvt_f32_f16_sdwa v87, v103 dst_sel:DWORD dst_unused:UNUSED_PAD src0_sel:WORD_1
	v_cvt_f32_f16_e32 v84, v104
	v_cvt_f32_f16_e32 v86, v103
	s_waitcnt lgkmcnt(0)
	v_cvt_f32_f16_sdwa v83, v105 dst_sel:DWORD dst_unused:UNUSED_PAD src0_sel:WORD_1
	v_cvt_f32_f16_e32 v82, v105
	v_pk_add_f32 v[78:79], v[78:79], v[88:89]
	v_pk_add_f32 v[80:81], v[80:81], v[86:87]
	v_pk_add_f32 v[84:85], v[74:75], v[84:85]
	v_cvt_pk_f16_f32 v74, v78, v79
	v_mul_f32_e32 v79, v79, v79
	v_fmac_f32_e32 v79, v78, v78
	v_mul_f32_e32 v78, v81, v81
	v_cvt_f32_f16_sdwa v95, v99 dst_sel:DWORD dst_unused:UNUSED_PAD src0_sel:WORD_1
	v_cvt_f32_f16_sdwa v97, v98 dst_sel:DWORD dst_unused:UNUSED_PAD src0_sel:WORD_1
	v_cvt_f32_f16_e32 v94, v99
	v_cvt_f32_f16_e32 v96, v98
	v_pk_add_f32 v[82:83], v[76:77], v[82:83]
	v_fmac_f32_e32 v78, v80, v80
	v_cvt_f32_f16_sdwa v91, v101 dst_sel:DWORD dst_unused:UNUSED_PAD src0_sel:WORD_1
	v_cvt_f32_f16_sdwa v93, v100 dst_sel:DWORD dst_unused:UNUSED_PAD src0_sel:WORD_1
	v_cvt_f32_f16_e32 v90, v101
	v_cvt_f32_f16_e32 v92, v100
	v_cvt_pk_f16_f32 v75, v80, v81
	v_add_f32_e32 v78, v79, v78
	v_mul_f32_e32 v79, v85, v85
	v_mul_f32_e32 v80, v83, v83
	v_fmac_f32_e32 v79, v84, v84
	v_fmac_f32_e32 v80, v82, v82
	v_add_f32_e32 v79, v79, v80
	v_cvt_pk_f16_f32 v77, v82, v83
	v_add_f32_e32 v82, v78, v79
	v_pk_add_f32 v[78:79], v[70:71], v[96:97]
	v_pk_add_f32 v[72:73], v[72:73], v[94:95]
	v_pk_add_f32 v[80:81], v[66:67], v[92:93]
	v_pk_add_f32 v[66:67], v[68:69], v[90:91]
	v_mul_f32_e32 v68, v79, v79
	v_mul_f32_e32 v69, v73, v73
	v_fmac_f32_e32 v68, v78, v78
	v_fmac_f32_e32 v69, v72, v72
	v_add_f32_e32 v68, v68, v69
	v_mul_f32_e32 v69, v81, v81
	v_mul_f32_e32 v70, v67, v67
	v_fmac_f32_e32 v69, v80, v80
	v_fmac_f32_e32 v70, v66, v66
	v_add_f32_e32 v69, v69, v70
	v_add_f32_e32 v68, v68, v69
	v_add_f32_e32 v70, v82, v68
	v_cvt_pk_f16_f32 v76, v84, v85
	v_mov_b32_e32 v84, v70
	s_nop 1
	v_permlane16_swap_b32_e32 v84, v70
	v_cvt_pk_f16_f32 v71, v66, v67
	v_lshl_add_u64 v[68:69], s[0:1], 0, v[108:109]
	v_lshl_add_u64 v[82:83], v[148:149], 1, v[68:69]
	v_cvt_pk_f16_f32 v69, v72, v73
	s_waitcnt lgkmcnt(0)
	v_add_f32_e32 v66, v70, v84
	v_mov_b32_e32 v67, v66
	s_nop 1
	v_permlane32_swap_b32_e32 v67, v66
	v_cvt_pk_f16_f32 v70, v80, v81
	v_cvt_pk_f16_f32 v68, v78, v79
	global_store_dwordx4 v[82:83], v[74:77], off
	global_store_dwordx4 v[82:83], v[68:71], off offset:256
	s_and_saveexec_b64 s[54:55], s[36:37]
	s_cbranch_execz .LBB0_356
	v_lshlrev_b64 v[68:69], 7, v[106:107]
	v_lshl_add_u64 v[68:69], s[44:45], 0, v[68:69]
	v_lshl_add_u64 v[68:69], s[52:53], 2, v[68:69]
	s_lshl_b32 s24, s23, 2
	v_lshl_add_u64 v[68:69], v[68:69], 0, s[24:25]
	s_waitcnt lgkmcnt(0)
	v_add_f32_e32 v66, v66, v67
	global_store_dword v[68:69], v66, off
;     __device__ __forceinline__ void operator()(const f32x4 (&acc)[2][2][4][2], const Unit& u, int wr, int wc, int fr, int fq) const {
;     ...
;         for (int ai = 0; ai < 2; ++ai)
; #pragma unroll
;         for (int mh = 0; mh < 2; ++mh) {
;             f32x8v pre[2][2];
;             if (base32) {
; #pragma unroll
;                 for (int mm = 0; mm < 2; ++mm) { const size_t off = (size_t)(row0 + ai * HALF + (2 * mh + mm) * 16) * ldc + col0;
; #pragma unroll
;                     for (int bj = 0; bj < 2; ++bj) { const f32x4 a0 = *(const f32x4*)(base32 + off + bj * HALF), a1 = *(const f32x4*)(base32 + off + bj * HALF + 4);
;                         pre[mm][bj] = __builtin_shufflevector(a0, a1, 0, 1, 2, 3, 4, 5, 6, 7); } }
;             } else if (pf & 1) {
; #pragma unroll
;                 for (int mm = 0; mm < 2; ++mm)
; #pragma unroll
;                     for (int bj = 0; bj < 2; ++bj) pre[mm][bj] = (f32x8v){0, 0, 0, 0, 0, 0, 0, 0};
;             } else {
;                 f16x8v ph[2][2];
; #pragma unroll
;                 for (int mm = 0; mm < 2; ++mm) { const size_t off = (size_t)(row0 + ai * HALF + (2 * mh + mm) * 16) * ldc + col0;
; #pragma unroll
;                     for (int bj = 0; bj < 2; ++bj) ph[mm][bj] = *(const f16x8v*)(xh + off + bj * HALF); }
; #pragma unroll
;                 for (int mm = 0; mm < 2; ++mm)
; #pragma unroll
;                     for (int bj = 0; bj < 2; ++bj) pre[mm][bj] = __builtin_convertvector(ph[mm][bj], f32x8v);
;             }
; #pragma unroll
;             for (int mm = 0; mm < 2; ++mm) {
;                 const int m = 2 * mh + mm;
;                 const int row = row0 + ai * HALF + m * 16; const size_t off = (size_t)row * ldc + col0;
;                 float q = 0.f;
; #pragma unroll
;                 for (int bj = 0; bj < 2; ++bj) {
;                     const f32x8v o = pre[mm][bj] + __builtin_shufflevector(acc[ai][bj][m][0], acc[ai][bj][m][1], 0, 1, 2, 3, 4, 5, 6, 7);
;                     if (!(pf & 2)) *(f16x8v*)(xh + off + bj * HALF) = __builtin_convertvector(o, f16x8v);
;                     q += ((o[0] * o[0] + o[1] * o[1]) + (o[2] * o[2] + o[3] * o[3])) + ((o[4] * o[4] + o[5] * o[5]) + (o[6] * o[6] + o[7] * o[7]));
;                 }
;                 if (!(pf & 4)) { q += __shfl_xor(q, 16); q += __shfl_xor(q, 32);
;                 if (fq == 0) ssn[(size_t)row * 32 + u.pn * 4 + wc] = q; }
.LBB0_356:
	s_or_b64 exec, exec, s[54:55]
	v_add_u32_e32 v78, 0x80, v150
	v_ashrrev_i32_e32 v79, 31, v78
	v_lshlrev_b64 v[88:89], 12, v[78:79]
	s_waitcnt lgkmcnt(0)
	v_lshl_add_u64 v[66:67], v[152:153], 0, v[88:89]
	s_waitcnt vmcnt(4)
	v_mov_b64_e32 v[80:81], v[204:205]
	v_mov_b64_e32 v[82:83], v[206:207]
	v_mov_b64_e32 v[84:85], v[208:209]
	v_mov_b64_e32 v[86:87], v[210:211]
	v_add_u32_e32 v74, 0x90, v150
	v_ashrrev_i32_e32 v75, 31, v74
	v_lshlrev_b64 v[76:77], 12, v[74:75]
	v_lshl_add_u64 v[66:67], v[152:153], 0, v[76:77]
	v_mov_b64_e32 v[70:71], v[212:213]
	v_mov_b64_e32 v[72:73], v[214:215]
	s_nop 0
	v_mov_b64_e32 v[66:67], v[216:217]
	v_mov_b64_e32 v[68:69], v[218:219]
	s_mov_b32 s54, 0xa0000
	s_mov_b32 s55, 0
	v_lshl_add_u64 v[220:221], v[222:223], 0, s[54:55]
	global_load_dwordx4 v[204:207], v[220:221], off
	global_load_dwordx4 v[208:211], v[220:221], off offset:256
	s_mov_b32 s54, 0xb0000
	v_lshl_add_u64 v[220:221], v[222:223], 0, s[54:55]
	global_load_dwordx4 v[212:215], v[220:221], off
	global_load_dwordx4 v[216:219], v[220:221], off offset:256
	v_cvt_f32_f16_e32 v90, v83
	v_cvt_f32_f16_sdwa v91, v83 dst_sel:DWORD dst_unused:UNUSED_PAD src0_sel:WORD_1
	v_cvt_f32_f16_e32 v92, v82
	v_cvt_f32_f16_sdwa v93, v82 dst_sel:DWORD dst_unused:UNUSED_PAD src0_sel:WORD_1
	v_cvt_f32_f16_e32 v82, v81
	v_cvt_f32_f16_sdwa v83, v81 dst_sel:DWORD dst_unused:UNUSED_PAD src0_sel:WORD_1
	v_cvt_f32_f16_e32 v94, v80
	v_cvt_f32_f16_sdwa v95, v80 dst_sel:DWORD dst_unused:UNUSED_PAD src0_sel:WORD_1
	v_cvt_f32_f16_e32 v80, v87
	v_cvt_f32_f16_sdwa v81, v87 dst_sel:DWORD dst_unused:UNUSED_PAD src0_sel:WORD_1
	v_cvt_f32_f16_e32 v96, v86
	v_cvt_f32_f16_sdwa v97, v86 dst_sel:DWORD dst_unused:UNUSED_PAD src0_sel:WORD_1
	v_cvt_f32_f16_e32 v86, v85
	v_cvt_f32_f16_sdwa v87, v85 dst_sel:DWORD dst_unused:UNUSED_PAD src0_sel:WORD_1
	v_cvt_f32_f16_e32 v98, v84
	v_cvt_f32_f16_sdwa v99, v84 dst_sel:DWORD dst_unused:UNUSED_PAD src0_sel:WORD_1
	v_pk_add_f32 v[62:63], v[62:63], v[94:95]
	v_pk_add_f32 v[64:65], v[64:65], v[82:83]
	v_pk_add_f32 v[58:59], v[58:59], v[92:93]
	v_pk_add_f32 v[60:61], v[60:61], v[90:91]
	v_pk_add_f32 v[82:83], v[54:55], v[98:99]
	v_pk_add_f32 v[56:57], v[56:57], v[86:87]
	v_pk_add_f32 v[84:85], v[50:51], v[96:97]
	v_pk_add_f32 v[54:55], v[52:53], v[80:81]
	v_cvt_pk_f16_f32 v53, v60, v61
	v_cvt_pk_f16_f32 v52, v58, v59
	v_cvt_pk_f16_f32 v51, v64, v65
	v_cvt_pk_f16_f32 v50, v62, v63
	v_mul_f32_e32 v63, v63, v63
	v_mul_f32_e32 v65, v65, v65
	v_mul_f32_e32 v59, v59, v59
	v_mul_f32_e32 v61, v61, v61
	v_mul_f32_e32 v80, v83, v83
	v_mul_f32_e32 v81, v57, v57
	v_mul_f32_e32 v86, v85, v85
	v_mul_f32_e32 v87, v55, v55
	v_fmac_f32_e32 v63, v62, v62
	v_fmac_f32_e32 v65, v64, v64
	v_fmac_f32_e32 v59, v58, v58
	v_fmac_f32_e32 v61, v60, v60
	v_fmac_f32_e32 v80, v82, v82
	v_fmac_f32_e32 v81, v56, v56
	v_fmac_f32_e32 v86, v84, v84
	v_fmac_f32_e32 v87, v54, v54
	v_add_f32_e32 v58, v63, v65
	v_add_f32_e32 v59, v59, v61
	v_add_f32_e32 v60, v80, v81
	v_add_f32_e32 v61, v86, v87
	v_add_f32_e32 v58, v58, v59
	v_add_f32_e32 v59, v60, v61
	v_add_f32_e32 v60, v58, v59
	v_mov_b32_e32 v61, v60
	s_nop 1
	v_permlane16_swap_b32_e32 v61, v60
	v_lshl_add_u64 v[58:59], s[0:1], 0, v[88:89]
	v_lshl_add_u64 v[58:59], v[148:149], 1, v[58:59]
	global_store_dwordx4 v[58:59], v[50:53], off
	v_cvt_pk_f16_f32 v55, v54, v55
	v_cvt_pk_f16_f32 v54, v84, v85
	s_waitcnt lgkmcnt(0)
	v_add_f32_e32 v50, v60, v61
	v_mov_b32_e32 v51, v50
	s_nop 1
	v_permlane32_swap_b32_e32 v51, v50
	v_cvt_pk_f16_f32 v53, v56, v57
	v_cvt_pk_f16_f32 v52, v82, v83
	global_store_dwordx4 v[58:59], v[52:55], off offset:256
	s_and_saveexec_b64 s[54:55], s[36:37]
	s_cbranch_execz .LBB0_358
	v_lshlrev_b64 v[52:53], 7, v[78:79]
	v_lshl_add_u64 v[52:53], s[44:45], 0, v[52:53]
	v_lshl_add_u64 v[52:53], s[52:53], 2, v[52:53]
	s_lshl_b32 s24, s23, 2
	v_lshl_add_u64 v[52:53], v[52:53], 0, s[24:25]
	s_waitcnt lgkmcnt(0)
	v_add_f32_e32 v50, v50, v51
	global_store_dword v[52:53], v50, off
.LBB0_358:
	s_or_b64 exec, exec, s[54:55]
	v_cvt_f32_f16_sdwa v57, v70 dst_sel:DWORD dst_unused:UNUSED_PAD src0_sel:WORD_1
	v_cvt_f32_f16_e32 v56, v70
	v_cvt_f32_f16_sdwa v53, v72 dst_sel:DWORD dst_unused:UNUSED_PAD src0_sel:WORD_1
	v_cvt_f32_f16_sdwa v55, v71 dst_sel:DWORD dst_unused:UNUSED_PAD src0_sel:WORD_1
	v_cvt_f32_f16_e32 v52, v72
	v_cvt_f32_f16_e32 v54, v71
	s_waitcnt lgkmcnt(0)
	v_cvt_f32_f16_sdwa v51, v73 dst_sel:DWORD dst_unused:UNUSED_PAD src0_sel:WORD_1
	v_cvt_f32_f16_e32 v50, v73
	v_pk_add_f32 v[46:47], v[46:47], v[56:57]
	v_pk_add_f32 v[48:49], v[48:49], v[54:55]
	v_pk_add_f32 v[52:53], v[42:43], v[52:53]
	v_cvt_pk_f16_f32 v42, v46, v47
	v_mul_f32_e32 v47, v47, v47
	v_fmac_f32_e32 v47, v46, v46
	v_mul_f32_e32 v46, v49, v49
	v_cvt_f32_f16_sdwa v63, v67 dst_sel:DWORD dst_unused:UNUSED_PAD src0_sel:WORD_1
	v_cvt_f32_f16_sdwa v65, v66 dst_sel:DWORD dst_unused:UNUSED_PAD src0_sel:WORD_1
	v_cvt_f32_f16_e32 v62, v67
	v_cvt_f32_f16_e32 v64, v66
	v_pk_add_f32 v[50:51], v[44:45], v[50:51]
	v_fmac_f32_e32 v46, v48, v48
	v_cvt_f32_f16_sdwa v59, v69 dst_sel:DWORD dst_unused:UNUSED_PAD src0_sel:WORD_1
	v_cvt_f32_f16_sdwa v61, v68 dst_sel:DWORD dst_unused:UNUSED_PAD src0_sel:WORD_1
	v_cvt_f32_f16_e32 v58, v69
	v_cvt_f32_f16_e32 v60, v68
	v_cvt_pk_f16_f32 v43, v48, v49
	v_add_f32_e32 v46, v47, v46
	v_mul_f32_e32 v47, v53, v53
	v_mul_f32_e32 v48, v51, v51
	v_fmac_f32_e32 v47, v52, v52
	v_fmac_f32_e32 v48, v50, v50
	v_add_f32_e32 v47, v47, v48
	v_cvt_pk_f16_f32 v45, v50, v51
	v_add_f32_e32 v50, v46, v47
	v_pk_add_f32 v[46:47], v[38:39], v[64:65]
	v_pk_add_f32 v[40:41], v[40:41], v[62:63]
	v_pk_add_f32 v[48:49], v[34:35], v[60:61]
	v_pk_add_f32 v[34:35], v[36:37], v[58:59]
	v_mul_f32_e32 v36, v47, v47
	v_mul_f32_e32 v37, v41, v41
	v_fmac_f32_e32 v36, v46, v46
	v_fmac_f32_e32 v37, v40, v40
	v_add_f32_e32 v36, v36, v37
	v_mul_f32_e32 v37, v49, v49
	v_mul_f32_e32 v38, v35, v35
	v_fmac_f32_e32 v37, v48, v48
	v_fmac_f32_e32 v38, v34, v34
	v_add_f32_e32 v37, v37, v38
	v_add_f32_e32 v36, v36, v37
	v_add_f32_e32 v38, v50, v36
	v_cvt_pk_f16_f32 v44, v52, v53
	v_mov_b32_e32 v52, v38
	s_nop 1
	v_permlane16_swap_b32_e32 v52, v38
	v_cvt_pk_f16_f32 v39, v34, v35
	v_lshl_add_u64 v[36:37], s[0:1], 0, v[76:77]
	v_lshl_add_u64 v[50:51], v[148:149], 1, v[36:37]
	v_cvt_pk_f16_f32 v37, v40, v41
	s_waitcnt lgkmcnt(0)
	v_add_f32_e32 v34, v38, v52
	v_mov_b32_e32 v35, v34
	s_nop 1
	v_permlane32_swap_b32_e32 v35, v34
	v_cvt_pk_f16_f32 v38, v48, v49
	v_cvt_pk_f16_f32 v36, v46, v47
	global_store_dwordx4 v[50:51], v[42:45], off
	global_store_dwordx4 v[50:51], v[36:39], off offset:256
	s_and_saveexec_b64 s[54:55], s[36:37]
	s_cbranch_execz .LBB0_360
	v_lshlrev_b64 v[36:37], 7, v[74:75]
	v_lshl_add_u64 v[36:37], s[44:45], 0, v[36:37]
	v_lshl_add_u64 v[36:37], s[52:53], 2, v[36:37]
	s_lshl_b32 s24, s23, 2
	v_lshl_add_u64 v[36:37], v[36:37], 0, s[24:25]
	s_waitcnt lgkmcnt(0)
	v_add_f32_e32 v34, v34, v35
	global_store_dword v[36:37], v34, off
;     __device__ __forceinline__ void operator()(const f32x4 (&acc)[2][2][4][2], const Unit& u, int wr, int wc, int fr, int fq) const {
;     ...
;         for (int ai = 0; ai < 2; ++ai)
; #pragma unroll
;         for (int mh = 0; mh < 2; ++mh) {
;             f32x8v pre[2][2];
;             if (base32) {
; #pragma unroll
;                 for (int mm = 0; mm < 2; ++mm) { const size_t off = (size_t)(row0 + ai * HALF + (2 * mh + mm) * 16) * ldc + col0;
; #pragma unroll
;                     for (int bj = 0; bj < 2; ++bj) { const f32x4 a0 = *(const f32x4*)(base32 + off + bj * HALF), a1 = *(const f32x4*)(base32 + off + bj * HALF + 4);
;                         pre[mm][bj] = __builtin_shufflevector(a0, a1, 0, 1, 2, 3, 4, 5, 6, 7); } }
;             } else if (pf & 1) {
; #pragma unroll
;                 for (int mm = 0; mm < 2; ++mm)
; #pragma unroll
;                     for (int bj = 0; bj < 2; ++bj) pre[mm][bj] = (f32x8v){0, 0, 0, 0, 0, 0, 0, 0};
;             } else {
;                 f16x8v ph[2][2];
; #pragma unroll
;                 for (int mm = 0; mm < 2; ++mm) { const size_t off = (size_t)(row0 + ai * HALF + (2 * mh + mm) * 16) * ldc + col0;
; #pragma unroll
;                     for (int bj = 0; bj < 2; ++bj) ph[mm][bj] = *(const f16x8v*)(xh + off + bj * HALF); }
; #pragma unroll
;                 for (int mm = 0; mm < 2; ++mm)
; #pragma unroll
;                     for (int bj = 0; bj < 2; ++bj) pre[mm][bj] = __builtin_convertvector(ph[mm][bj], f32x8v);
;             }
; #pragma unroll
;             for (int mm = 0; mm < 2; ++mm) {
;                 const int m = 2 * mh + mm;
;                 const int row = row0 + ai * HALF + m * 16; const size_t off = (size_t)row * ldc + col0;
;                 float q = 0.f;
; #pragma unroll
;                 for (int bj = 0; bj < 2; ++bj) {
;                     const f32x8v o = pre[mm][bj] + __builtin_shufflevector(acc[ai][bj][m][0], acc[ai][bj][m][1], 0, 1, 2, 3, 4, 5, 6, 7);
;                     if (!(pf & 2)) *(f16x8v*)(xh + off + bj * HALF) = __builtin_convertvector(o, f16x8v);
;                     q += ((o[0] * o[0] + o[1] * o[1]) + (o[2] * o[2] + o[3] * o[3])) + ((o[4] * o[4] + o[5] * o[5]) + (o[6] * o[6] + o[7] * o[7]));
;                 }
;                 if (!(pf & 4)) { q += __shfl_xor(q, 16); q += __shfl_xor(q, 32);
;                 if (fq == 0) ssn[(size_t)row * 32 + u.pn * 4 + wc] = q; }
.LBB0_360:
	s_or_b64 exec, exec, s[54:55]
	v_add_u32_e32 v46, 0xa0, v150
	v_ashrrev_i32_e32 v47, 31, v46
	v_lshlrev_b64 v[56:57], 12, v[46:47]
	s_waitcnt lgkmcnt(0)
	v_lshl_add_u64 v[34:35], v[152:153], 0, v[56:57]
	s_waitcnt vmcnt(4)
	v_mov_b64_e32 v[48:49], v[204:205]
	v_mov_b64_e32 v[50:51], v[206:207]
	v_mov_b64_e32 v[52:53], v[208:209]
	v_mov_b64_e32 v[54:55], v[210:211]
	v_add_u32_e32 v42, 0xb0, v150
	v_ashrrev_i32_e32 v43, 31, v42
	v_lshlrev_b64 v[44:45], 12, v[42:43]
	v_lshl_add_u64 v[34:35], v[152:153], 0, v[44:45]
	v_mov_b64_e32 v[38:39], v[212:213]
	v_mov_b64_e32 v[40:41], v[214:215]
	s_nop 0
	v_mov_b64_e32 v[34:35], v[216:217]
	v_mov_b64_e32 v[36:37], v[218:219]
	v_cvt_f32_f16_e32 v58, v51
	v_cvt_f32_f16_sdwa v59, v51 dst_sel:DWORD dst_unused:UNUSED_PAD src0_sel:WORD_1
	v_cvt_f32_f16_e32 v60, v50
	v_cvt_f32_f16_sdwa v61, v50 dst_sel:DWORD dst_unused:UNUSED_PAD src0_sel:WORD_1
	v_cvt_f32_f16_e32 v50, v49
	v_cvt_f32_f16_sdwa v51, v49 dst_sel:DWORD dst_unused:UNUSED_PAD src0_sel:WORD_1
	v_cvt_f32_f16_e32 v62, v48
	v_cvt_f32_f16_sdwa v63, v48 dst_sel:DWORD dst_unused:UNUSED_PAD src0_sel:WORD_1
	v_cvt_f32_f16_e32 v48, v55
	v_cvt_f32_f16_sdwa v49, v55 dst_sel:DWORD dst_unused:UNUSED_PAD src0_sel:WORD_1
	v_cvt_f32_f16_e32 v64, v54
	v_cvt_f32_f16_sdwa v65, v54 dst_sel:DWORD dst_unused:UNUSED_PAD src0_sel:WORD_1
	v_cvt_f32_f16_e32 v54, v53
	v_cvt_f32_f16_sdwa v55, v53 dst_sel:DWORD dst_unused:UNUSED_PAD src0_sel:WORD_1
	v_cvt_f32_f16_e32 v66, v52
	v_cvt_f32_f16_sdwa v67, v52 dst_sel:DWORD dst_unused:UNUSED_PAD src0_sel:WORD_1
	v_pk_add_f32 v[30:31], v[30:31], v[62:63]
	v_pk_add_f32 v[32:33], v[32:33], v[50:51]
	v_pk_add_f32 v[26:27], v[26:27], v[60:61]
	v_pk_add_f32 v[28:29], v[28:29], v[58:59]
	v_pk_add_f32 v[50:51], v[22:23], v[66:67]
	v_pk_add_f32 v[24:25], v[24:25], v[54:55]
	v_pk_add_f32 v[52:53], v[18:19], v[64:65]
	v_pk_add_f32 v[22:23], v[20:21], v[48:49]
	v_cvt_pk_f16_f32 v21, v28, v29
	v_cvt_pk_f16_f32 v20, v26, v27
	v_cvt_pk_f16_f32 v19, v32, v33
	v_cvt_pk_f16_f32 v18, v30, v31
	v_mul_f32_e32 v31, v31, v31
	v_mul_f32_e32 v33, v33, v33
	v_mul_f32_e32 v27, v27, v27
	v_mul_f32_e32 v29, v29, v29
	v_mul_f32_e32 v48, v51, v51
	v_mul_f32_e32 v49, v25, v25
	v_mul_f32_e32 v54, v53, v53
	v_mul_f32_e32 v55, v23, v23
	v_fmac_f32_e32 v31, v30, v30
	v_fmac_f32_e32 v33, v32, v32
	v_fmac_f32_e32 v27, v26, v26
	v_fmac_f32_e32 v29, v28, v28
	v_fmac_f32_e32 v48, v50, v50
	v_fmac_f32_e32 v49, v24, v24
	v_fmac_f32_e32 v54, v52, v52
	v_fmac_f32_e32 v55, v22, v22
	v_add_f32_e32 v26, v31, v33
	v_add_f32_e32 v27, v27, v29
	v_add_f32_e32 v28, v48, v49
	v_add_f32_e32 v29, v54, v55
	v_add_f32_e32 v26, v26, v27
	v_add_f32_e32 v27, v28, v29
	v_add_f32_e32 v28, v26, v27
	v_mov_b32_e32 v29, v28
	s_nop 1
	v_permlane16_swap_b32_e32 v29, v28
	v_lshl_add_u64 v[26:27], s[0:1], 0, v[56:57]
	v_lshl_add_u64 v[26:27], v[148:149], 1, v[26:27]
	global_store_dwordx4 v[26:27], v[18:21], off
	v_cvt_pk_f16_f32 v23, v22, v23
	v_cvt_pk_f16_f32 v22, v52, v53
	s_waitcnt lgkmcnt(0)
	v_add_f32_e32 v18, v28, v29
	v_mov_b32_e32 v19, v18
	s_nop 1
	v_permlane32_swap_b32_e32 v19, v18
	v_cvt_pk_f16_f32 v21, v24, v25
	v_cvt_pk_f16_f32 v20, v50, v51
	global_store_dwordx4 v[26:27], v[20:23], off offset:256
	s_and_saveexec_b64 s[54:55], s[36:37]
	s_cbranch_execz .LBB0_362
	v_lshlrev_b64 v[20:21], 7, v[46:47]
	v_lshl_add_u64 v[20:21], s[44:45], 0, v[20:21]
	v_lshl_add_u64 v[20:21], s[52:53], 2, v[20:21]
	s_lshl_b32 s24, s23, 2
	v_lshl_add_u64 v[20:21], v[20:21], 0, s[24:25]
	s_waitcnt lgkmcnt(0)
	v_add_f32_e32 v18, v18, v19
	global_store_dword v[20:21], v18, off
.LBB0_362:
	s_or_b64 exec, exec, s[54:55]
	v_cvt_f32_f16_sdwa v25, v38 dst_sel:DWORD dst_unused:UNUSED_PAD src0_sel:WORD_1
	v_cvt_f32_f16_e32 v24, v38
	v_cvt_f32_f16_sdwa v21, v40 dst_sel:DWORD dst_unused:UNUSED_PAD src0_sel:WORD_1
	v_cvt_f32_f16_sdwa v23, v39 dst_sel:DWORD dst_unused:UNUSED_PAD src0_sel:WORD_1
	v_cvt_f32_f16_e32 v20, v40
	v_cvt_f32_f16_e32 v22, v39
	s_waitcnt lgkmcnt(0)
	v_cvt_f32_f16_sdwa v19, v41 dst_sel:DWORD dst_unused:UNUSED_PAD src0_sel:WORD_1
	v_cvt_f32_f16_e32 v18, v41
	v_pk_add_f32 v[14:15], v[14:15], v[24:25]
	v_pk_add_f32 v[16:17], v[16:17], v[22:23]
	v_pk_add_f32 v[20:21], v[10:11], v[20:21]
	v_cvt_pk_f16_f32 v10, v14, v15
	v_mul_f32_e32 v15, v15, v15
	v_fmac_f32_e32 v15, v14, v14
	v_mul_f32_e32 v14, v17, v17
	v_cvt_f32_f16_sdwa v31, v35 dst_sel:DWORD dst_unused:UNUSED_PAD src0_sel:WORD_1
	v_cvt_f32_f16_sdwa v33, v34 dst_sel:DWORD dst_unused:UNUSED_PAD src0_sel:WORD_1
	v_cvt_f32_f16_e32 v30, v35
	v_cvt_f32_f16_e32 v32, v34
	v_pk_add_f32 v[18:19], v[12:13], v[18:19]
	v_fmac_f32_e32 v14, v16, v16
	v_cvt_f32_f16_sdwa v27, v37 dst_sel:DWORD dst_unused:UNUSED_PAD src0_sel:WORD_1
	v_cvt_f32_f16_sdwa v29, v36 dst_sel:DWORD dst_unused:UNUSED_PAD src0_sel:WORD_1
	v_cvt_f32_f16_e32 v26, v37
	v_cvt_f32_f16_e32 v28, v36
	v_cvt_pk_f16_f32 v11, v16, v17
	v_add_f32_e32 v14, v15, v14
	v_mul_f32_e32 v15, v21, v21
	v_mul_f32_e32 v16, v19, v19
	v_fmac_f32_e32 v15, v20, v20
	v_fmac_f32_e32 v16, v18, v18
	v_add_f32_e32 v15, v15, v16
	v_cvt_pk_f16_f32 v13, v18, v19
	v_add_f32_e32 v18, v14, v15
	v_pk_add_f32 v[14:15], v[6:7], v[32:33]
	v_pk_add_f32 v[8:9], v[8:9], v[30:31]
	v_pk_add_f32 v[16:17], v[2:3], v[28:29]
	v_pk_add_f32 v[2:3], v[4:5], v[26:27]
	v_mul_f32_e32 v4, v15, v15
	v_mul_f32_e32 v5, v9, v9
	v_fmac_f32_e32 v4, v14, v14
	v_fmac_f32_e32 v5, v8, v8
	v_add_f32_e32 v4, v4, v5
	v_mul_f32_e32 v5, v17, v17
	v_mul_f32_e32 v6, v3, v3
	v_fmac_f32_e32 v5, v16, v16
	v_fmac_f32_e32 v6, v2, v2
	v_add_f32_e32 v5, v5, v6
	v_add_f32_e32 v4, v4, v5
	v_add_f32_e32 v6, v18, v4
	v_cvt_pk_f16_f32 v12, v20, v21
	v_mov_b32_e32 v20, v6
	s_nop 1
	v_permlane16_swap_b32_e32 v20, v6
	v_cvt_pk_f16_f32 v7, v2, v3
	v_lshl_add_u64 v[4:5], s[0:1], 0, v[44:45]
	v_lshl_add_u64 v[18:19], v[148:149], 1, v[4:5]
	v_cvt_pk_f16_f32 v5, v8, v9
	s_waitcnt lgkmcnt(0)
	v_add_f32_e32 v2, v6, v20
	v_mov_b32_e32 v3, v2
	s_nop 1
	v_permlane32_swap_b32_e32 v3, v2
	v_cvt_pk_f16_f32 v6, v16, v17
	v_cvt_pk_f16_f32 v4, v14, v15
	global_store_dwordx4 v[18:19], v[10:13], off
	global_store_dwordx4 v[18:19], v[4:7], off offset:256
	s_and_saveexec_b64 s[54:55], s[36:37]
	s_cbranch_execz .LBB0_364
	v_lshlrev_b64 v[4:5], 7, v[42:43]
	v_lshl_add_u64 v[4:5], s[44:45], 0, v[4:5]
	v_lshl_add_u64 v[4:5], s[52:53], 2, v[4:5]
	s_lshl_b32 s24, s23, 2
	v_lshl_add_u64 v[4:5], v[4:5], 0, s[24:25]
	s_waitcnt lgkmcnt(0)
	v_add_f32_e32 v2, v2, v3
	global_store_dword v[4:5], v2, off
